# phase 3: blocks warm the GLA state rows (an input) of their later items into L2 while the first item runs
# baseline (speedup 1.0000x reference)
; DEVINL int tidx() { int t = threadIdx.x; asm volatile("" : "+v"(t)); return t; }
; DEVINL void gla_passB(const Params& p, int idx) {
;   const int chain = idx >> 2, dvg = idx & 3;
;   const int tid = tidx(), dv = dvg * 32 + (tid & 31), d0 = (tid >> 5) * 8;
;   float S[8];
;   int item0, nchunks; float* outp;
;   if (chain < 32) {
;     item0 = chain * 33; nchunks = 33;
;     outp = p.out + OUT_GP + (size_t)chain * 8192;
; #pragma unroll
;     for (int i = 0; i < 8; ++i) S[i] = 0.f;
;   } else {
;     int bh = chain - 32;
;     item0 = NCH_P + bh; nchunks = 1;
;     outp = p.out + OUT_GS + (size_t)bh * 8192;
; #pragma unroll
;     for (int i = 0; i < 8; ++i) S[i] = p.state_gla[(size_t)bh * 8192 + (d0 + i) * 128 + dv];
;   }
; DEVINL void run_phase(const Params& p, char* smem, int ph) {
;     ...
;     case 3:
;       for (int it = bid; it < S5CP_BLK + GLAB_ITEMS + S5CS_BLK; it += nb) {
;         if (it < S5CP_BLK) { __syncthreads(); s5_passC_prompt(p, smem, it); }
;         else if (it < S5CP_BLK + GLAB_ITEMS) gla_passB(p, it - S5CP_BLK);
.LBB0_448:
	s_and_b64 vcc, exec, s[0:1]
	s_cbranch_vccz .LBB0_534
	s_cmpk_gt_i32 s14, 0xe7f
	s_cbranch_scc1 .LBB0_533
	s_lshl_b32 s0, s14, 5
	s_addk_i32 s0, 0xc000
	s_waitcnt vmcnt(0)
	s_cmpk_lt_u32 s14, 0x80
	s_cbranch_scc1 .LP3W_done
	v_and_b32_e32 v196, 31, v0
	v_lshrrev_b32_e32 v197, 5, v0
	v_lshlrev_b32_e32 v197, 12, v197
	v_lshl_or_b32 v196, v196, 2, v197
	v_mov_b32_e32 v198, s14
.LP3W_loop:
	v_lshrrev_b32_e32 v199, 2, v198
	v_subrev_u32_e32 v199, 32, v199
	v_lshlrev_b32_e32 v199, 15, v199
	v_and_b32_e32 v200, 3, v198
	v_lshl_add_u32 v199, v200, 7, v199
	v_add_u32_e32 v199, v199, v196
	global_load_dword v204, v199, s[56:57]
	global_load_dword v205, v199, s[56:57] offset:512
	global_load_dword v206, v199, s[56:57] offset:1024
	global_load_dword v207, v199, s[56:57] offset:1536
	global_load_dword v208, v199, s[56:57] offset:2048
	global_load_dword v209, v199, s[56:57] offset:2560
	global_load_dword v210, v199, s[56:57] offset:3072
	global_load_dword v211, v199, s[56:57] offset:3584
	v_add_u32_e32 v198, 0x180, v198
	v_cmp_gt_u32_e32 vcc, 0x880, v198
	s_cbranch_vccnz .LP3W_loop
.LP3W_done:
	v_lshlrev_b32_e32 v1, 5, v104
	s_mov_b64 s[40:41], 0
	s_waitcnt lgkmcnt(0)
	v_mov_b32_e32 v75, s14
	v_mov_b32_e32 v78, s0
	v_mov_b32_e32 v79, s14
	s_branch .LBB0_453
